# LRU: predecessor flag polled at unit start by wave 0 and carry loaded early when already published
# speedup vs baseline: 1.0116x; 1.0116x over previous
; #define LAS __attribute__((address_space(3)))
;     __device__ __forceinline__ int nt(const Unit& u, int) const { return (u.pn >> 2) == 0 ? 4 : 8; }
; __device__ __forceinline__ void lru_unit(const Ctx& C, const Params& p, int l, int unit) {
;     const int tc = unit >> 6, b = (unit >> 3) & 7, nb = unit & 7, c0 = nb * 64;
;     const bf16* Zb = (const bf16*)(C.ws + WS_Z) + (size_t)b * SEQ * ZC;
;     bf16* Ob = (bf16*)(C.ws + WS_O) + (size_t)b * SEQ * OC;
;     float* carr = (float*)(C.ws + WS_LC) + (size_t)(l * 1024) * 64;
;     unsigned* flg = (unsigned*)(C.ws + WS_LF) + (size_t)(l * 1024) * 16;
;     LAS unsigned char* XCB = C.lds;
;     LAS float* RF = (LAS float*)(C.lds + 18432);
;     LAS float* IF = (LAS float*)(C.lds + 18432 + 32768);
;     LAS float* AGG = (LAS float*)(C.lds + 83968);
;     LAS float* CAR = (LAS float*)(C.lds + 88064);
;     LAS float* CARP = (LAS float*)(C.lds + 88320);
;     LAS float* CIN = (LAS float*)(C.lds + 88576);
;     LAS bf16* HL = (LAS bf16*)(C.lds + 90112);
;     LAS bf16* PGL = (LAS bf16*)(C.lds + 122880);
;     const int tid = C.tid, lane = C.lane, i16 = lane & 15, g = lane >> 4, c = tid & 63, tg = tid >> 6;
;     const int ch = c0 + c;
;     const float* cwp = p.in[4] + (size_t)l * 4 * 512;
;     const float cw0 = cwp[ch], cw1 = cwp[512 + ch], cw2 = cwp[1024 + ch], cw3 = cwp[1536 + ch];
;     const float cb = p.in[5][l * 512 + ch], ba = p.in[7][l * 512 + ch], bx = p.in[9][l * 512 + ch];
;     const float lam = p.in[10][l * 512 + ch];
;     const float logu = -8.0f * log1pf(expf(-lam));
;     const bf16* WaT = (const bf16*)wla_ptr(C.ws, l) + nb * 4096;
;     const bf16* WxT = (const bf16*)wlx_ptr(C.ws, l) + nb * 4096;
;     bf16x8 wa[4][2], wx[4][2];
; #pragma unroll
;     for (int nt = 0; nt < 4; ++nt)
; #pragma unroll
;         for (int ks = 0; ks < 2; ++ks) { wa[nt][ks] = *(const bf16x8*)(WaT + (16 * nt + i16) * 64 + 32 * ks + 8 * g); wx[nt][ks] = *(const bf16x8*)(WxT + (16 * nt + i16) * 64 + 32 * ks + 8 * g); }
;     if (tid < 64) { CAR[tid] = 0.f; CARP[tid] = 1.f; }
;     ...
;             unsigned* pf = flg + (size_t)(unit - 64) * 16;
;             while (__hip_atomic_load(pf, __ATOMIC_RELAXED, __HIP_MEMORY_SCOPE_AGENT) == 0u) __builtin_amdgcn_s_sleep(2);
;             cin = __hip_atomic_load(carr + (size_t)(unit - 64) * 64 + tid, __ATOMIC_RELAXED, __HIP_MEMORY_SCOPE_AGENT);
.LBB0_321:
	s_or_b64 exec, exec, s[40:41]
	s_waitcnt lgkmcnt(0)
	s_barrier
	ds_read_b32 v0, v193
	s_movk_i32 s19, 0x9ff
	s_mov_b64 s[40:41], -1
	s_waitcnt lgkmcnt(0)
	s_barrier
	v_cmp_lt_i32_e32 vcc, s19, v0
	v_readfirstlane_b32 s74, v0
	s_cbranch_vccnz .LBB0_316
	s_add_i32 s19, s74, 0xfffffe00
	s_ashr_i32 s72, s73, 6
	s_ashr_i32 s19, s19, 7
	s_and_b32 s20, s74, 0x7f
	s_cmpk_gt_i32 s74, 0x1ff
	s_cselect_b64 s[6:7], -1, 0
	s_cmp_lt_u32 s20, 64
	s_cselect_b64 s[22:23], -1, 0
	v_and_b32_e32 v169, 63, v132
	s_and_b64 s[22:23], s[6:7], s[22:23]
	s_andn2_b64 vcc, exec, s[22:23]
	v_lshrrev_b32_e32 v186, 4, v169
	s_cbranch_vccnz .LBB0_381
	s_cmp_lg_u32 s72, 0
	s_cbranch_scc1 .Llru_pf1_skip
	s_cmp_lt_i32 s19, 1
	s_cbranch_scc1 .Llru_pf1_skip
	s_lshl_b32 s100, s19, 6
	s_or_b32 s100, s100, s20
	s_sub_i32 s100, s100, 64
	s_lshl_b32 s100, s100, 6
	s_add_u32 s100, s100, s64
	s_addc_u32 s101, s65, 0
	s_add_u32 s100, s100, s8
	s_addc_u32 s101, s101, s9
	s_add_u32 s100, s100, 0x180000
	s_addc_u32 s101, s101, 0
	global_load_dword v206, v193, s[100:101] sc1
.Llru_pf1_skip:
	s_and_b32 s21, s74, 7
	s_lshl_b32 s56, s21, 6
	v_or_b32_e32 v114, s56, v169
	s_lshl_b32 s22, s20, 9
	v_lshlrev_b32_e32 v192, 2, v114
	v_readlane_b32 s0, v247, 13
	s_and_b32 s57, s22, 0x7000
	v_lshl_add_u64 v[0:1], s[60:61], 0, v[192:193]
	global_load_dword v115, v192, s[60:61]
	global_load_dword v116, v192, s[60:61] offset:2048
	v_or_b32_e32 v192, s0, v114
	v_readlane_b32 s0, v247, 10
	s_add_u32 s22, s64, s0
	s_addc_u32 s23, s65, 0
	s_lshl_b32 s21, s21, 13
	s_add_u32 s22, s22, s21
	v_add_co_u32_e32 v0, vcc, 0x1000, v0
	s_addc_u32 s23, s23, 0
	v_readlane_b32 s0, v247, 16
	v_addc_co_u32_e32 v1, vcc, 0, v1, vcc
	v_readlane_b32 s40, v249, 42
	s_add_u32 s24, s64, s0
	global_load_dword v117, v[0:1], off
	global_load_dword v118, v[0:1], off offset:2048
	v_lshlrev_b64 v[0:1], 2, v[192:193]
	v_readlane_b32 s50, v249, 52
	v_readlane_b32 s51, v249, 53
	s_addc_u32 s25, s65, 0
	v_readlane_b32 s41, v249, 43
	v_readlane_b32 s42, v249, 44
	v_readlane_b32 s43, v249, 45
	v_readlane_b32 s44, v249, 46
	v_readlane_b32 s45, v249, 47
	v_readlane_b32 s46, v249, 48
	v_readlane_b32 s47, v249, 49
	v_readlane_b32 s48, v249, 50
	v_readlane_b32 s49, v249, 51
	v_readlane_b32 s52, v249, 54
	v_readlane_b32 s53, v249, 55
	v_readlane_b32 s54, v249, 56
	v_readlane_b32 s55, v249, 57
	v_lshl_add_u64 v[2:3], s[50:51], 0, v[0:1]
	s_add_u32 s24, s24, s21
	v_and_b32_e32 v64, 15, v132
	global_load_dword v119, v[2:3], off
	v_lshl_add_u64 v[2:3], s[54:55], 0, v[0:1]
	v_readlane_b32 s40, v250, 10
	s_addc_u32 s25, s25, 0
	v_and_b32_e32 v192, 48, v169
	v_readlane_b32 s42, v250, 12
	v_readlane_b32 s43, v250, 13
	v_readlane_b32 s44, v250, 14
	v_readlane_b32 s45, v250, 15
	v_lshl_add_u64 v[48:49], s[22:23], 0, v[192:193]
	v_lshl_add_u64 v[50:51], s[24:25], 0, v[192:193]
	v_lshlrev_b32_e32 v192, 7, v64
	global_load_dword v120, v[2:3], off
	v_lshl_add_u64 v[2:3], s[42:43], 0, v[0:1]
	v_lshl_add_u64 v[0:1], s[44:45], 0, v[0:1]
	s_waitcnt vmcnt(12)
	v_lshl_add_u64 v[20:21], v[48:49], 0, v[192:193]
	s_waitcnt vmcnt(10)
	v_lshl_add_u64 v[28:29], v[50:51], 0, v[192:193]
	global_load_dword v121, v[2:3], off
	global_load_dword v65, v[0:1], off
	s_nop 0
	global_load_dwordx4 v[0:3], v[20:21], off
	global_load_dwordx4 v[4:7], v[20:21], off offset:64
	global_load_dwordx4 v[8:11], v[28:29], off
	global_load_dwordx4 v[12:15], v[28:29], off offset:64
	global_load_dwordx4 v[16:19], v[20:21], off offset:2048
	s_nop 0
	global_load_dwordx4 v[20:23], v[20:21], off offset:2112
	s_nop 0
	global_load_dwordx4 v[24:27], v[28:29], off offset:2048
	s_nop 0
	global_load_dwordx4 v[28:31], v[28:29], off offset:2112
	v_or_b32_e32 v32, 0x1000, v192
	v_mov_b32_e32 v33, v193
	v_or_b32_e32 v192, 0x1800, v192
	v_lshl_add_u64 v[36:37], v[48:49], 0, v[32:33]
	v_lshl_add_u64 v[44:45], v[50:51], 0, v[32:33]
	v_lshl_add_u64 v[52:53], v[48:49], 0, v[192:193]
	v_lshl_add_u64 v[60:61], v[50:51], 0, v[192:193]
	global_load_dwordx4 v[32:35], v[36:37], off
	s_nop 0
	global_load_dwordx4 v[36:39], v[36:37], off offset:64
	s_nop 0
	global_load_dwordx4 v[40:43], v[44:45], off
	s_nop 0
	global_load_dwordx4 v[44:47], v[44:45], off offset:64
	s_nop 0
	global_load_dwordx4 v[48:51], v[52:53], off
	s_nop 0
	global_load_dwordx4 v[52:55], v[52:53], off offset:64
	s_nop 0
	global_load_dwordx4 v[56:59], v[60:61], off
	s_nop 0
	global_load_dwordx4 v[60:63], v[60:61], off offset:64
	v_readlane_b32 s41, v250, 11
	v_cmp_gt_i32_e64 s[40:41], 64, v132
	v_readlane_b32 s46, v250, 16
	v_readlane_b32 s47, v250, 17
	v_readlane_b32 s48, v250, 18
	v_readlane_b32 s49, v250, 19
	v_readlane_b32 s50, v250, 20
	v_readlane_b32 s51, v250, 21
	v_readlane_b32 s52, v250, 22
	v_readlane_b32 s53, v250, 23
	v_readlane_b32 s54, v250, 24
	v_readlane_b32 s55, v250, 25
	s_and_saveexec_b64 s[42:43], s[40:41]
	s_cbranch_execz .LBB0_325
	v_lshl_add_u32 v66, v132, 2, 0
	v_add_u32_e32 v67, 0x15840, v66
	v_add_u32_e32 v66, 0x15940, v66
	ds_write_b32 v67, v193
	ds_write_b32 v66, v232
.LBB0_325:
	s_or_b64 exec, exec, s[42:43]
	s_waitcnt vmcnt(16)
	s_cmp_lg_u32 s72, 0
	s_cbranch_scc1 .Llru_pf2_skip
	s_cmp_lt_i32 s19, 1
	s_cbranch_scc1 .Llru_pf2_skip
	v_readfirstlane_b32 s100, v206
	v_mov_b32_e32 v206, 0
	s_cmp_lg_u32 s100, 0
	s_cbranch_scc0 .Llru_pf2_skip
	s_lshl_b32 s100, s19, 6
	s_or_b32 s100, s100, s20
	s_sub_i32 s100, s100, 64
	s_lshl_b32 s100, s100, 8
	v_lshl_add_u32 v208, v132, 2, s100
	v_readlane_b32 s100, v247, 17
	v_readlane_b32 s101, v247, 18
	s_nop 1
	s_add_u32 s100, s100, s64
	s_addc_u32 s101, s101, s65
	s_add_u32 s100, s100, 0x100000
	s_addc_u32 s101, s101, 0
	v_mov_b32_e32 v206, 1
	global_load_dword v207, v208, s[100:101] sc1
;     __device__ __forceinline__ int nt(const Unit& u, int) const { return (u.pn >> 2) == 0 ? 4 : 8; }
; __device__ __forceinline__ void lru_unit(const Ctx& C, const Params& p, int l, int unit) {
;     ...
;     const float* cwp = p.in[4] + (size_t)l * 4 * 512;
;     const float cw0 = cwp[ch], cw1 = cwp[512 + ch], cw2 = cwp[1024 + ch], cw3 = cwp[1536 + ch];
;     const float cb = p.in[5][l * 512 + ch], ba = p.in[7][l * 512 + ch], bx = p.in[9][l * 512 + ch];
;     const float lam = p.in[10][l * 512 + ch];
;     const float logu = -8.0f * log1pf(expf(-lam));
;     const bf16* WaT = (const bf16*)wla_ptr(C.ws, l) + nb * 4096;
;     const bf16* WxT = (const bf16*)wlx_ptr(C.ws, l) + nb * 4096;
;     bf16x8 wa[4][2], wx[4][2];
; #pragma unroll
;     for (int nt = 0; nt < 4; ++nt)
; #pragma unroll
;         for (int ks = 0; ks < 2; ++ks) { wa[nt][ks] = *(const bf16x8*)(WaT + (16 * nt + i16) * 64 + 32 * ks + 8 * g); wx[nt][ks] = *(const bf16x8*)(WxT + (16 * nt + i16) * 64 + 32 * ks + 8 * g); }
;     if (tid < 64) { CAR[tid] = 0.f; CARP[tid] = 1.f; }
;     __syncthreads();
.Llru_pf2_skip:
	v_mul_f32_e32 v66, 0xbfb8aa3b, v65
	v_rndne_f32_e32 v67, v66
	s_mov_b32 s21, 0xbfb8aa3b
	v_sub_f32_e32 v68, v66, v67
	v_fma_f32 v66, v65, s21, -v66
	v_fmac_f32_e32 v66, 0xb2a5705f, v65
	v_add_f32_e32 v66, v68, v66
	v_exp_f32_e32 v66, v66
	v_cvt_i32_f32_e32 v67, v67
	s_mov_b32 s22, 0x42ce8ed0
	v_cmp_nlt_f32_e32 vcc, s22, v65
	s_mov_b32 s22, 0xc2b17218
	v_ldexp_f32 v66, v66, v67
	v_cndmask_b32_e32 v66, 0, v66, vcc
	v_cmp_ngt_f32_e32 vcc, s22, v65
	s_mov_b32 s22, 0x3f2aaaab
	s_mul_i32 s21, s57, 0x2600
	v_cndmask_b32_e32 v65, v236, v66, vcc
	v_add_f32_e32 v68, 1.0, v65
	v_add_f32_e32 v66, -1.0, v68
	v_sub_f32_e32 v67, v66, v68
	v_add_f32_e32 v67, 1.0, v67
	v_sub_f32_e32 v66, v65, v66
	v_add_f32_e32 v69, v66, v67
	v_frexp_mant_f32_e32 v70, v68
	v_cvt_f64_f32_e32 v[66:67], v68
	v_frexp_exp_i32_f64_e32 v66, v[66:67]
	v_cmp_gt_f32_e32 vcc, s22, v70
	s_mov_b32 s22, 0x3f317218
	s_add_u32 s21, s64, s21
	v_subbrev_co_u32_e32 v66, vcc, 0, v66, vcc
	v_sub_u32_e32 v67, 0, v66
	v_ldexp_f32 v68, v68, v67
	v_ldexp_f32 v67, v69, v67
	v_add_f32_e32 v69, -1.0, v68
	v_add_f32_e32 v72, 1.0, v68
	v_add_f32_e32 v70, 1.0, v69
	v_add_f32_e32 v73, -1.0, v72
	v_sub_f32_e32 v70, v68, v70
	v_sub_f32_e32 v68, v68, v73
	v_add_f32_e32 v70, v67, v70
	v_add_f32_e32 v67, v67, v68
	v_add_f32_e32 v68, v72, v67
	v_rcp_f32_e32 v73, v68
	v_add_f32_e32 v71, v69, v70
	v_sub_f32_e32 v69, v69, v71
	v_add_f32_e32 v69, v70, v69
	v_sub_f32_e32 v70, v72, v68
	v_add_f32_e32 v67, v67, v70
	v_mul_f32_e32 v70, v71, v73
	v_mul_f32_e32 v72, v68, v70
	v_fma_f32 v74, v70, v68, -v72
	v_fmac_f32_e32 v74, v70, v67
	v_add_f32_e32 v75, v72, v74
	v_sub_f32_e32 v76, v71, v75
	v_sub_f32_e32 v71, v71, v76
	v_sub_f32_e32 v72, v75, v72
	v_sub_f32_e32 v71, v71, v75
	v_add_f32_e32 v69, v69, v71
	v_sub_f32_e32 v71, v72, v74
	v_add_f32_e32 v69, v71, v69
	v_add_f32_e32 v71, v76, v69
	v_mul_f32_e32 v72, v73, v71
	v_mul_f32_e32 v74, v68, v72
	v_fma_f32 v68, v72, v68, -v74
	v_fmac_f32_e32 v68, v72, v67
	v_sub_f32_e32 v67, v76, v71
	v_add_f32_e32 v67, v69, v67
	v_add_f32_e32 v69, v74, v68
	v_sub_f32_e32 v75, v71, v69
	v_sub_f32_e32 v71, v71, v75
	v_sub_f32_e32 v74, v69, v74
	v_sub_f32_e32 v69, v71, v69
	v_add_f32_e32 v67, v67, v69
	v_sub_f32_e32 v68, v74, v68
	v_cvt_f32_i32_e32 v66, v66
	v_add_f32_e32 v67, v68, v67
	v_add_f32_e32 v68, v70, v72
	v_add_f32_e32 v67, v75, v67
	v_sub_f32_e32 v69, v68, v70
	v_mul_f32_e32 v67, v73, v67
	v_sub_f32_e32 v69, v72, v69
	v_add_f32_e32 v67, v69, v67
	v_mul_f32_e32 v72, 0x3f317218, v66
	v_add_f32_e32 v69, v68, v67
	v_fma_f32 v73, v66, s22, -v72
	v_mul_f32_e32 v70, v69, v69
	v_fmac_f32_e32 v73, 0xb102e308, v66
	v_sub_f32_e32 v66, v69, v68
	v_fmamk_f32 v71, v70, 0x3e9b6dac, v233
	v_sub_f32_e32 v66, v67, v66
	v_add_f32_e32 v67, v72, v73
	v_fmaak_f32 v71, v70, v71, 0x3f2aaada
	v_sub_f32_e32 v68, v67, v72
	v_ldexp_f32 v72, v69, 1
	v_mul_f32_e32 v69, v69, v70
	v_mul_f32_e32 v69, v69, v71
	v_add_f32_e32 v70, v72, v69
	v_sub_f32_e32 v71, v70, v72
	v_ldexp_f32 v66, v66, 1
	v_sub_f32_e32 v69, v69, v71
	v_add_f32_e32 v66, v66, v69
	v_add_f32_e32 v69, v70, v66
	v_sub_f32_e32 v70, v69, v70
	v_sub_f32_e32 v66, v66, v70
	v_add_f32_e32 v70, v67, v69
	v_sub_f32_e32 v71, v70, v67
	v_sub_f32_e32 v72, v70, v71
	v_sub_f32_e32 v68, v73, v68
	v_sub_f32_e32 v67, v67, v72
	v_sub_f32_e32 v69, v69, v71
	v_add_f32_e32 v67, v69, v67
	v_add_f32_e32 v69, v68, v66
	v_sub_f32_e32 v71, v69, v68
	v_sub_f32_e32 v72, v69, v71
	v_sub_f32_e32 v68, v68, v72
	v_sub_f32_e32 v66, v66, v71
	v_add_f32_e32 v67, v69, v67
	v_add_f32_e32 v66, v66, v68
	v_add_f32_e32 v68, v70, v67
	v_sub_f32_e32 v69, v68, v70
	v_sub_f32_e32 v67, v67, v69
	v_add_f32_e32 v66, v66, v67
	v_add_f32_e32 v66, v68, v66
	v_cmp_neq_f32_e32 vcc, s75, v65
	s_mov_b32 s22, 0x33800000
	v_ashrrev_i32_e32 v123, 6, v132
	v_cndmask_b32_e32 v66, v236, v66, vcc
	v_cmp_lt_f32_e64 vcc, |v65|, s22
	s_addc_u32 s22, s65, 0
	s_add_u32 s50, s21, 0xbc00000
	s_addc_u32 s51, s22, 0
	v_lshlrev_b32_e32 v68, 2, v169
	s_add_i32 s22, 0, 0x15840
	v_lshlrev_b32_e32 v125, 4, v123
	v_add_u32_e32 v126, s22, v68
	s_add_i32 s22, 0, 0x15940
	v_add_u32_e32 v127, s22, v68
	s_movk_i32 s22, 0x900
	v_or_b32_e32 v70, 1, v125
	v_lshl_or_b32 v72, v123, 12, v68
	v_cndmask_b32_e32 v65, v66, v65, vcc
	v_and_b32_e32 v66, 48, v132
	v_lshl_add_u32 v67, v64, 2, 0
	v_mul_lo_u32 v69, v123, s22
	s_movk_i32 s0, 0x90
	v_add_u32_e32 v128, 0, v72
	v_lshl_or_b32 v68, v70, 8, v68
	v_lshl_or_b32 v64, s72, 4, v64
	s_lshl_b32 s22, s72, 12
	v_mul_f32_e32 v124, 0xc1000000, v65
	v_lshl_add_u32 v65, v169, 1, 0
	v_add_u32_e32 v66, 0, v66
	v_mul_lo_u32 v71, v70, s0
	v_add_u32_e32 v68, 0, v68
	v_add_u32_e32 v70, 0x200, v128
	v_add_u32_e32 v72, 0x300, v128
	v_add_u32_e32 v73, 0x400, v128
	v_add_u32_e32 v74, 0x500, v128
	v_add_u32_e32 v75, 0x600, v128
	v_add_u32_e32 v76, 0x700, v128
	v_add_u32_e32 v77, 0x800, v128
	v_add_u32_e32 v78, 0x900, v128
	v_add_u32_e32 v79, 0xa00, v128
	v_add_u32_e32 v80, 0xb00, v128
	v_add_u32_e32 v81, 0xc00, v128
	v_add_u32_e32 v82, 0xd00, v128
	v_add_u32_e32 v83, 0xe00, v128
	v_add_u32_e32 v84, 0xf00, v128
	v_mul_lo_u32 v64, v64, s0
	v_lshl_or_b32 v85, v186, 10, s22
	v_readlane_b32 s0, v248, 56
	s_mov_b32 s24, 0
	s_lshl_b32 s21, s19, 8
	v_lshlrev_b32_e32 v122, 3, v132
	v_cmp_lt_i32_e64 s[42:43], 0, v123
	v_cmp_eq_u32_e64 s[44:45], 7, v123
	v_lshl_add_u32 v129, v169, 3, s0
	s_mov_b64 s[52:53], -1
	v_add_u32_e32 v130, v65, v69
	v_add_u32_e32 v131, v65, v71
	v_add_u32_e32 v133, v66, v64
	v_add_u32_e32 v134, v67, v85
	v_add_u32_e32 v135, 64, v68
	v_add_u32_e32 v136, 64, v70
	v_add_u32_e32 v137, 64, v72
	v_add_u32_e32 v138, 64, v73
	v_add_u32_e32 v139, 64, v74
	v_add_u32_e32 v140, 64, v75
	v_add_u32_e32 v141, 64, v76
	v_add_u32_e32 v142, 64, v77
	v_add_u32_e32 v143, 64, v78
	v_add_u32_e32 v144, 64, v79
	v_add_u32_e32 v145, 64, v80
	v_add_u32_e32 v146, 64, v81
	v_add_u32_e32 v147, 64, v82
	v_add_u32_e32 v148, 64, v83
	v_add_u32_e32 v149, 64, v84
	s_waitcnt lgkmcnt(0)
	s_barrier
	s_branch .LBB0_327

; __device__ __forceinline__ void lru_unit(const Ctx& C, const Params& p, int l, int unit) {
;     ...
;     __syncthreads();
;     if (tid < 64) {
;         float cin = 0.f;
;         if (tc > 0) {
;             unsigned* pf = flg + (size_t)(unit - 64) * 16;
;             while (__hip_atomic_load(pf, __ATOMIC_RELAXED, __HIP_MEMORY_SCOPE_AGENT) == 0u) __builtin_amdgcn_s_sleep(2);
;             cin = __hip_atomic_load(carr + (size_t)(unit - 64) * 64 + tid, __ATOMIC_RELAXED, __HIP_MEMORY_SCOPE_AGENT);
;         }
;         CIN[tid] = cin;
;         if (tc < 15) {
;             __hip_atomic_store(carr + (size_t)unit * 64 + tid, CARP[tid] * cin + CAR[tid], __ATOMIC_RELAXED, __HIP_MEMORY_SCOPE_AGENT);
;             asm volatile("s_waitcnt vmcnt(0)" ::: "memory");
;             if (tid == 0) __hip_atomic_store(flg + (size_t)unit * 16, 1u, __ATOMIC_RELAXED, __HIP_MEMORY_SCOPE_AGENT);
;         }
;     }
.LBB0_371:
	s_waitcnt lgkmcnt(0)
	s_barrier
	s_and_saveexec_b64 s[42:43], s[40:41]
	s_cbranch_execz .LBB0_380
	s_lshl_b32 s24, s19, 6
	s_or_b32 s40, s24, s20
	v_readlane_b32 s0, v247, 17
	v_readlane_b32 s1, v247, 18
	s_add_u32 s24, s64, s0
	s_addc_u32 s25, s65, s1
	s_add_u32 s26, s24, 0x100000
	s_addc_u32 s27, s25, 0
	s_mov_b64 s[0:1], s[8:9]
	s_add_u32 s24, s64, s0
	s_addc_u32 s25, s65, s1
	s_add_u32 s24, s24, 0x180000
	s_addc_u32 s25, s25, 0
	s_cmp_lt_i32 s19, 1
	s_cbranch_scc1 .LBB0_376
	v_readfirstlane_b32 s28, v206
	s_cmp_lg_u32 s28, 0
	s_cbranch_scc0 .Llru_pf3_none
	v_mov_b32_e32 v0, v207
	s_branch .LBB0_377
.Llru_pf3_none:
	s_sub_i32 s36, s40, 64
	s_lshl_b64 s[28:29], s[36:37], 6
	s_add_u32 s44, s24, s28
	s_addc_u32 s45, s25, s29
	global_load_dword v0, v193, s[44:45] sc1
	s_waitcnt vmcnt(0)
	v_cmp_ne_u32_e32 vcc, 0, v0
	s_cbranch_vccnz .LBB0_375
